# stack3 + P3b GDN p4 items ordered newest snapshots first (p3border)
# speedup vs baseline: 1.0231x; 1.0023x over previous
.LBB0_1029:
	s_cmpk_gt_i32 s2, 0xfff
	s_cbranch_scc1 .LBB0_1032
	s_add_u32 s15, s20, 0x17348000
	s_addc_u32 s16, s21, 0
	s_add_u32 s100, s20, 0x10000
	s_addc_u32 s101, s21, 0
	s_waitcnt vmcnt(30)
	v_mbcnt_hi_u32_b32 v20, -1, v183
	s_add_u32 s17, s20, 0x15248000
	v_and_b32_e32 v0, 64, v20
	s_mov_b32 s0, 0x358637bd
	s_addc_u32 s29, s21, 0
	s_mov_b32 s9, 0
	v_mov_b32_e32 v9, 0
	s_mov_b64 s[10:11], 0x1000
	s_mov_b64 s[12:13], 0x1800
	s_movk_i32 s34, 0x1000
	v_xor_b32_e32 v21, 1, v20
	v_add_u32_e32 v22, 64, v0
	v_xor_b32_e32 v23, 2, v20
	s_waitcnt vmcnt(29)
	v_xor_b32_e32 v24, 4, v20
	v_xor_b32_e32 v25, 8, v20
	s_mov_b32 s14, 0x3c800000
	v_mov_b64_e32 v[10:11], s[0:1]
	s_mov_b32 s35, 0x800000
	s_movk_i32 s36, 0x2000
	s_movk_i32 s37, 0x4000
	s_movk_i32 s38, 0x6000
	s_add_i32 s39, s2, 0x200
	s_mov_b32 s72, 0x55555555
	s_mov_b32 s73, 0x55555555
.LBB0_1031:
	v_cmp_lt_i32_e32 vcc, v21, v22
	v_mov_b32_e32 v0, v181
	s_ashr_i32 s0, s39, 3
	v_cndmask_b32_e32 v2, v20, v21, vcc
	v_cmp_lt_i32_e32 vcc, v23, v22
	s_waitcnt vmcnt(28)
	v_lshlrev_b32_e32 v33, 2, v2
	v_ashrrev_i32_e32 v2, 6, v0
	v_cndmask_b32_e32 v3, v20, v23, vcc
	v_cmp_lt_i32_e32 vcc, v24, v22
	v_lshlrev_b32_e32 v32, 2, v3
	v_and_b32_e32 v3, 63, v0
	v_cndmask_b32_e32 v4, v20, v24, vcc
	v_cmp_lt_i32_e32 vcc, v25, v22
	v_lshlrev_b32_e32 v31, 2, v4
	v_and_b32_e32 v4, 15, v0
	v_cndmask_b32_e32 v5, v20, v25, vcc
	v_lshlrev_b32_e32 v30, 2, v5
	v_lshrrev_b32_e32 v0, 2, v0
	v_lshlrev_b32_e32 v5, 4, v2
	s_lshl_b32 s1, s39, 7
	v_and_b32_e32 v6, 12, v0
	v_lshlrev_b32_e32 v7, 2, v3
	v_lshlrev_b32_e32 v12, 5, v3
	v_lshl_add_u32 v3, s0, 6, v5
	s_and_b32 s4, s39, 0xfffffc00
	s_and_b32 s8, s1, 0x380
	v_lshlrev_b32_e32 v8, 1, v4
	v_lshlrev_b32_e32 v0, 2, v4
	v_or_b32_e32 v5, v5, v4
	v_or_b32_e32 v4, v3, v6
	s_and_b32 s1, s0, 0x7f
	s_or_b32 s4, s8, s4
	global_load_dword v29, v0, s[40:41]
	global_load_dword v28, v0, s[40:41] offset:64
	global_load_dword v27, v0, s[40:41] offset:128
	global_load_dword v26, v0, s[40:41] offset:192
	v_lshlrev_b32_e32 v0, 1, v6
	v_lshlrev_b32_e32 v6, 6, v5
	v_ashrrev_i32_e32 v5, 31, v4
	s_or_b32 s4, s4, s1
	s_waitcnt vmcnt(28)
	v_lshlrev_b64 v[66:67], 13, v[4:5]
	s_ashr_i32 s5, s4, 31
	v_or_b32_e32 v14, 1, v4
	v_or_b32_e32 v16, 2, v4
	v_or_b32_e32 v18, 3, v4
	v_lshl_add_u64 v[4:5], s[20:21], 0, v[66:67]
	s_lshl_b64 s[0:1], s[4:5], 13
	v_lshl_add_u64 v[4:5], v[4:5], 0, s[8:9]
	s_add_u32 s4, s50, s0
	v_lshl_add_u64 v[50:51], v[4:5], 0, v[8:9]
	s_addc_u32 s5, s51, s1
	v_add_co_u32_e32 v52, vcc, s36, v50
	s_add_u32 s6, s17, s0
	s_nop 0
	v_addc_co_u32_e32 v53, vcc, 0, v51, vcc
	v_lshl_or_b32 v2, v2, 10, v7
	v_ashrrev_i32_e32 v7, 31, v6
	s_addc_u32 s7, s29, s1
	v_add_co_u32_e32 v54, vcc, s37, v50
	v_mov_b32_e32 v1, v9
	v_ashrrev_i32_e32 v3, 31, v2
	v_lshl_add_u64 v[6:7], v[6:7], 1, s[4:5]
	s_add_u32 s0, s15, s0
	v_addc_co_u32_e32 v55, vcc, 0, v51, vcc
	v_mov_b32_e32 v13, v9
	v_lshl_add_u64 v[34:35], v[6:7], 0, v[0:1]
	v_lshl_add_u64 v[36:37], v[2:3], 1, s[6:7]
	s_addc_u32 s1, s16, s1
	v_add_co_u32_e32 v56, vcc, s38, v50
	global_load_dwordx2 v[4:5], v[34:35], off
	global_load_dwordx2 v[6:7], v[34:35], off offset:32
	global_load_dwordx2 v[0:1], v[34:35], off offset:64
	global_load_dwordx2 v[2:3], v[34:35], off offset:96
	global_load_dwordx2 v[68:69], v[36:37], off
	global_load_dwordx2 v[72:73], v[36:37], off offset:512
	global_load_dwordx2 v[76:77], v[36:37], off offset:1024
	global_load_dwordx2 v[80:81], v[36:37], off offset:1536
	v_addc_co_u32_e32 v57, vcc, 0, v51, vcc
	global_load_ushort v82, v[50:51], off offset:3072
	global_load_ushort v83, v[50:51], off offset:3104
	global_load_ushort v84, v[50:51], off offset:3136
	global_load_ushort v85, v[50:51], off offset:3168
	global_load_dwordx4 v[34:37], v12, s[0:1]
	global_load_dwordx4 v[38:41], v12, s[0:1] offset:2048
	global_load_dwordx4 v[42:45], v12, s[0:1] offset:16
	global_load_dwordx4 v[46:49], v12, s[0:1] offset:2064
	global_load_ushort v86, v[52:53], off offset:3072
	global_load_ushort v87, v[54:55], off offset:3072
	global_load_ushort v88, v[56:57], off offset:3072
	global_load_ushort v89, v[52:53], off offset:3104
	global_load_ushort v90, v[54:55], off offset:3104
	global_load_ushort v91, v[56:57], off offset:3104
	global_load_ushort v92, v[52:53], off offset:3136
	global_load_ushort v93, v[54:55], off offset:3136
	global_load_ushort v94, v[56:57], off offset:3136
	global_load_ushort v95, v[54:55], off offset:3168
	global_load_ushort v96, v[52:53], off offset:3168
	global_load_ushort v97, v[56:57], off offset:3168
	v_lshl_add_u64 v[12:13], s[0:1], 0, v[12:13]
	v_lshl_add_u64 v[70:71], v[12:13], 0, s[10:11]
	s_waitcnt vmcnt(55)
	v_lshl_add_u64 v[74:75], v[12:13], 0, s[12:13]
	v_add_co_u32_e32 v12, vcc, s34, v12
	s_add_u32 s0, s20, s8
	s_nop 0
	v_addc_co_u32_e32 v13, vcc, 0, v13, vcc
	global_load_dwordx4 v[50:53], v[12:13], off
	global_load_dwordx4 v[54:57], v[12:13], off offset:2048
	global_load_dwordx4 v[58:61], v[70:71], off offset:16
	global_load_dwordx4 v[62:65], v[74:75], off offset:16
	s_addc_u32 s1, s21, 0
	v_and_b32_e32 v12, 0xffe00000, v66
	v_lshrrev_b32_e32 v13, 5, v66
	v_and_b32_e32 v13, 0xe000, v13
	v_lshrrev_b32_e32 v14, 7, v66
	v_and_b32_e32 v14, 0x7c0, v14
	v_lshrrev_b32_e32 v15, 10, v66
	v_and_b32_e32 v15, 32, v15
	v_and_b32_e32 v16, 30, v8
	v_or3_b32 v12, v12, v13, v14
	v_or3_b32 v12, v12, v15, v16
	s_lshl_b32 s8, s8, 10
	v_add_u32_e32 v12, s8, v12
	v_xor_b32_e32 v16, 16, v12
	v_add_u32_e32 v14, 64, v12
	v_add_u32_e32 v18, 0xc0, v16
	v_add_u32_e32 v16, 0x80, v16
	v_xor_b32_e32 v13, 32, v12
	v_xor_b32_e32 v15, 32, v14
	v_xor_b32_e32 v17, 32, v16
	v_xor_b32_e32 v19, 32, v18
	v_add_u32_e32 v14, -2, v14
	v_add_u32_e32 v15, -2, v15
	v_add_u32_e32 v18, -2, v18
	v_add_u32_e32 v19, -2, v19
	v_cndmask_b32_e64 v12, v14, v12, s[72:73]
	v_cndmask_b32_e64 v13, v15, v13, s[72:73]
	v_cndmask_b32_e64 v16, v18, v16, s[72:73]
	v_cndmask_b32_e64 v17, v19, v17, s[72:73]
	s_add_i32 s8, s39, 0x400
	s_cmpk_lt_i32 s8, 0x1000
	s_cbranch_scc1 .Lp3b_nx
	s_and_b32 s8, s39, 0x1ff
	s_bitcmp1_b32 s39, 9
.Lp3b_nx:
	s_mov_b32 s39, s8
	s_waitcnt vmcnt(23)
	v_lshlrev_b32_e32 v8, 16, v82
	s_waitcnt vmcnt(22)
	v_lshlrev_b32_e32 v98, 16, v83
	s_waitcnt vmcnt(21)
	v_lshlrev_b32_e32 v99, 16, v84
	s_waitcnt vmcnt(20)
	v_lshlrev_b32_e32 v100, 16, v85
	s_waitcnt vmcnt(19)
	v_mov_b32_e32 v82, v34
	v_mov_b32_e32 v83, v35
	s_waitcnt vmcnt(18)
	v_mov_b32_e32 v84, v38
	v_mov_b32_e32 v85, v39
	s_waitcnt vmcnt(17)
	v_mov_b32_e32 v34, v42
	v_mov_b32_e32 v35, v43
	v_mul_f32_e32 v42, 0xbfb8aa3b, v8
	v_mul_f32_e32 v43, 0xbfb8aa3b, v98
	v_mov_b32_e32 v38, v36
	v_mov_b32_e32 v39, v37
	v_lshlrev_b32_e32 v66, 16, v68
	v_and_b32_e32 v67, 0xffff0000, v68
	v_lshlrev_b32_e32 v68, 16, v69
	v_and_b32_e32 v69, 0xffff0000, v69
	v_lshlrev_b32_e32 v70, 16, v72
	v_and_b32_e32 v71, 0xffff0000, v72
	v_lshlrev_b32_e32 v72, 16, v73
	v_and_b32_e32 v73, 0xffff0000, v73
	s_waitcnt vmcnt(16)
	v_mov_b32_e32 v36, v46
	v_mov_b32_e32 v37, v47
	v_mov_b32_e32 v46, v44
	v_mov_b32_e32 v47, v45
	v_exp_f32_e32 v103, v42
	v_exp_f32_e32 v107, v43
	v_mfma_f32_16x16x32_bf16 v[42:45], v[4:7], v[82:85], v[66:69]
	v_lshlrev_b32_e32 v74, 16, v76
	v_and_b32_e32 v75, 0xffff0000, v76
	v_lshlrev_b32_e32 v76, 16, v77
	v_and_b32_e32 v77, 0xffff0000, v77
	v_lshlrev_b32_e32 v78, 16, v80
	v_and_b32_e32 v79, 0xffff0000, v80
	v_lshlrev_b32_e32 v80, 16, v81
	v_and_b32_e32 v81, 0xffff0000, v81
	s_waitcnt vmcnt(15)
	v_lshlrev_b32_e32 v86, 16, v86
	s_waitcnt vmcnt(14)
	v_lshlrev_b32_e32 v87, 16, v87
	v_mul_f32_e32 v101, 0xbfb8aa3b, v99
	v_mfma_f32_16x16x32_bf16 v[38:41], v[4:7], v[38:41], v[70:73]
	s_waitcnt vmcnt(8)
	v_lshlrev_b32_e32 v93, 16, v93
	s_waitcnt vmcnt(7)
	v_lshlrev_b32_e32 v94, 16, v94
	v_mul_f32_e32 v104, 0xbfb8aa3b, v86
	v_mul_f32_e32 v105, 0xbfb8aa3b, v87
	v_exp_f32_e32 v67, v101
	v_mfma_f32_16x16x32_bf16 v[34:37], v[4:7], v[34:37], v[74:77]
	v_lshlrev_b32_e32 v88, 16, v88
	v_lshlrev_b32_e32 v89, 16, v89
	v_lshlrev_b32_e32 v90, 16, v90
	v_mfma_f32_16x16x32_bf16 v[4:7], v[4:7], v[46:49], v[78:81]
	v_lshlrev_b32_e32 v92, 16, v92
	s_waitcnt vmcnt(5)
	v_lshlrev_b32_e32 v96, 16, v96
	v_lshlrev_b32_e32 v95, 16, v95
	v_mul_f32_e32 v69, 0xbfb8aa3b, v93
	v_mul_f32_e32 v70, 0xbfb8aa3b, v94
	s_waitcnt vmcnt(3)
	v_mov_b32_e32 v46, v50
	v_mov_b32_e32 v47, v51
	s_waitcnt vmcnt(2)
	v_mov_b32_e32 v48, v54
	v_mov_b32_e32 v49, v55
	s_waitcnt vmcnt(1)
	v_mov_b32_e32 v50, v58
	v_mov_b32_e32 v51, v59
	v_exp_f32_e32 v58, v104
	v_exp_f32_e32 v59, v105
	v_lshlrev_b32_e32 v91, 16, v91
	v_mul_f32_e32 v102, 0xbfb8aa3b, v100
	v_lshlrev_b32_e32 v97, 16, v97
	v_mul_f32_e32 v106, 0xbfb8aa3b, v88
	v_mul_f32_e32 v108, 0xbfb8aa3b, v89
	v_mul_f32_e32 v109, 0xbfb8aa3b, v90
	v_mul_f32_e32 v68, 0xbfb8aa3b, v92
	v_mul_f32_e32 v72, 0xbfb8aa3b, v96
	v_mul_f32_e32 v73, 0xbfb8aa3b, v95
	v_mov_b32_e32 v54, v52
	v_mov_b32_e32 v55, v53
	v_mfma_f32_16x16x32_bf16 v[42:45], v[0:3], v[46:49], v[42:45]
	v_exp_f32_e32 v46, v69
	v_exp_f32_e32 v47, v70
	v_mul_f32_e32 v66, 0xbfb8aa3b, v91
	v_exp_f32_e32 v71, v102
	v_mul_f32_e32 v74, 0xbfb8aa3b, v97
	s_waitcnt vmcnt(0)
	v_mov_b32_e32 v52, v62
	v_mov_b32_e32 v53, v63
	v_mov_b32_e32 v62, v60
	v_mov_b32_e32 v63, v61
	v_exp_f32_e32 v60, v106
	v_exp_f32_e32 v61, v108
	v_exp_f32_e32 v75, v109
	v_exp_f32_e32 v68, v68
	v_exp_f32_e32 v48, v72
	v_mfma_f32_16x16x32_bf16 v[38:41], v[0:3], v[54:57], v[38:41]
	v_exp_f32_e32 v49, v73
	v_exp_f32_e32 v66, v66
	v_exp_f32_e32 v54, v74
	v_add_f32_e32 v55, 1.0, v103
	v_mfma_f32_16x16x32_bf16 v[34:37], v[0:3], v[50:53], v[34:37]
	v_add_f32_e32 v50, 1.0, v107
	v_add_f32_e32 v51, 1.0, v67
	v_add_f32_e32 v46, 1.0, v46
	v_mfma_f32_16x16x32_bf16 v[0:3], v[0:3], v[62:65], v[4:7]
	v_rcp_f32_e32 v62, v55
	v_add_f32_e32 v47, 1.0, v47
	v_add_f32_e32 v52, 1.0, v71
	v_add_f32_e32 v4, 1.0, v58
	v_add_f32_e32 v5, 1.0, v59
	v_rcp_f32_e32 v58, v50
	v_rcp_f32_e32 v59, v51
	v_add_f32_e32 v6, 1.0, v60
	v_add_f32_e32 v7, 1.0, v61
	v_add_f32_e32 v50, 1.0, v75
	v_add_f32_e32 v51, 1.0, v68
	v_add_f32_e32 v48, 1.0, v48
	v_add_f32_e32 v49, 1.0, v49
	v_rcp_f32_e32 v61, v4
	v_rcp_f32_e32 v63, v5
	v_rcp_f32_e32 v69, v46
	v_rcp_f32_e32 v70, v47
	v_mov_b32_e32 v4, v42
	v_mov_b32_e32 v5, v38
	v_mov_b32_e32 v46, v43
	v_mov_b32_e32 v47, v39
	v_add_f32_e32 v53, 1.0, v66
	v_rcp_f32_e32 v60, v52
	v_add_f32_e32 v52, 1.0, v54
	v_rcp_f32_e32 v64, v6
	v_rcp_f32_e32 v65, v7
	v_rcp_f32_e32 v66, v50
	v_rcp_f32_e32 v68, v51
	v_rcp_f32_e32 v71, v48
	v_rcp_f32_e32 v72, v49
	v_mov_b32_e32 v6, v34
	v_mov_b32_e32 v7, v0
	v_mov_b32_e32 v48, v35
	v_mov_b32_e32 v49, v1
	v_mov_b32_e32 v50, v44
	v_mov_b32_e32 v51, v40
	v_mov_b32_e32 v54, v45
	v_mov_b32_e32 v55, v41
	v_pk_mul_f32 v[4:5], v[4:5], v[4:5]
	v_pk_mul_f32 v[46:47], v[46:47], v[46:47]
	v_rcp_f32_e32 v67, v53
	v_rcp_f32_e32 v73, v52
	v_mov_b32_e32 v52, v36
	v_mov_b32_e32 v53, v2
	v_mov_b32_e32 v56, v37
	v_mov_b32_e32 v57, v3
	v_mul_f32_e32 v8, v62, v8
	v_mul_f32_e32 v62, v58, v98
	v_mul_f32_e32 v74, v59, v99
	v_pk_mul_f32 v[6:7], v[6:7], v[6:7]
	v_pk_mul_f32 v[48:49], v[48:49], v[48:49]
	v_pk_mul_f32 v[50:51], v[50:51], v[50:51]
	v_pk_mul_f32 v[54:55], v[54:55], v[54:55]
	v_mov_b32_e32 v58, v46
	v_mov_b32_e32 v59, v4
	v_mov_b32_e32 v4, v47
	v_pk_mul_f32 v[52:53], v[52:53], v[52:53]
	v_pk_mul_f32 v[56:57], v[56:57], v[56:57]
	v_mov_b32_e32 v46, v48
	v_mov_b32_e32 v47, v6
	v_mov_b32_e32 v6, v49
	v_mov_b32_e32 v48, v54
	v_mov_b32_e32 v49, v50
	v_mov_b32_e32 v50, v55
	v_pk_add_f32 v[4:5], v[58:59], v[4:5]
	v_mov_b32_e32 v54, v56
	v_mov_b32_e32 v55, v52
	v_pk_add_f32 v[48:49], v[48:49], v[50:51]
	v_pk_add_f32 v[4:5], v[4:5], v[46:47]
	v_mov_b32_e32 v52, v57
	v_pk_add_f32 v[46:47], v[48:49], v[54:55]
	v_pk_add_f32 v[4:5], v[4:5], v[6:7]
	v_pk_add_f32 v[6:7], v[46:47], v[52:53]
	ds_bpermute_b32 v47, v33, v5
	ds_bpermute_b32 v46, v33, v4
	ds_bpermute_b32 v49, v33, v7
	ds_bpermute_b32 v48, v33, v6
	v_mul_f32_e32 v60, v60, v100
	v_mul_f32_e32 v61, v61, v86
	s_waitcnt lgkmcnt(2)
	v_pk_add_f32 v[4:5], v[4:5], v[46:47]
	ds_bpermute_b32 v47, v32, v5
	s_waitcnt lgkmcnt(1)
	v_pk_add_f32 v[6:7], v[6:7], v[48:49]
	ds_bpermute_b32 v46, v32, v4
	ds_bpermute_b32 v33, v32, v7
	ds_bpermute_b32 v32, v32, v6
	v_mul_f32_e32 v63, v63, v87
	v_mul_f32_e32 v64, v64, v88
	s_waitcnt lgkmcnt(2)
	v_pk_add_f32 v[4:5], v[4:5], v[46:47]
	v_mul_f32_e32 v65, v65, v89
	s_waitcnt lgkmcnt(0)
	v_pk_add_f32 v[6:7], v[6:7], v[32:33]
	ds_bpermute_b32 v33, v31, v5
	ds_bpermute_b32 v32, v31, v4
	ds_bpermute_b32 v47, v31, v7
	ds_bpermute_b32 v46, v31, v6
	v_mul_f32_e32 v66, v66, v90
	v_mul_f32_e32 v67, v67, v91
	s_waitcnt lgkmcnt(2)
	v_pk_add_f32 v[4:5], v[4:5], v[32:33]
	ds_bpermute_b32 v33, v30, v5
	s_waitcnt lgkmcnt(1)
	v_pk_add_f32 v[6:7], v[6:7], v[46:47]
	ds_bpermute_b32 v32, v30, v4
	ds_bpermute_b32 v31, v30, v7
	ds_bpermute_b32 v30, v30, v6
	v_mul_f32_e32 v68, v68, v92
	v_mul_f32_e32 v69, v69, v93
	s_waitcnt lgkmcnt(2)
	v_pk_add_f32 v[4:5], v[4:5], v[32:33]
	v_mul_f32_e32 v70, v70, v94
	s_waitcnt lgkmcnt(0)
	v_pk_add_f32 v[6:7], v[6:7], v[30:31]
	v_pk_fma_f32 v[4:5], v[4:5], s[14:15], v[10:11] op_sel_hi:[1,0,0]
	v_pk_fma_f32 v[6:7], v[6:7], s[14:15], v[10:11] op_sel_hi:[1,0,0]
	v_mul_f32_e32 v30, 0x4b800000, v5
	v_cmp_gt_f32_e64 s[6:7], s35, v5
	v_mul_f32_e32 v31, 0x4b800000, v4
	v_cmp_gt_f32_e32 vcc, s35, v4
	v_mul_f32_e32 v32, 0x4b800000, v7
	v_mul_f32_e32 v33, 0x4b800000, v6
	v_cmp_gt_f32_e64 s[0:1], s35, v6
	v_cmp_gt_f32_e64 s[4:5], s35, v7
	v_cndmask_b32_e64 v5, v5, v30, s[6:7]
	v_cndmask_b32_e32 v4, v4, v31, vcc
	v_cndmask_b32_e64 v7, v7, v32, s[4:5]
	v_cndmask_b32_e64 v6, v6, v33, s[0:1]
	v_rsq_f32_e32 v5, v5
	v_rsq_f32_e32 v4, v4
	v_rsq_f32_e32 v7, v7
	v_rsq_f32_e32 v6, v6
	v_mul_f32_e32 v30, 0x45800000, v5
	v_mul_f32_e32 v31, 0x45800000, v4
	v_mul_f32_e32 v32, 0x45800000, v7
	v_mul_f32_e32 v33, 0x45800000, v6
	v_cndmask_b32_e64 v5, v5, v30, s[6:7]
	v_cndmask_b32_e32 v4, v4, v31, vcc
	v_cndmask_b32_e64 v7, v7, v32, s[4:5]
	v_cndmask_b32_e64 v6, v6, v33, s[0:1]
	v_mul_f32_e32 v30, v42, v5
	v_mul_f32_e32 v31, v43, v4
	v_mul_f32_e32 v32, v44, v7
	v_mul_f32_e32 v33, v45, v6
	v_mul_f32_e32 v38, v38, v5
	v_mul_f32_e32 v39, v39, v4
	v_mul_f32_e32 v40, v40, v7
	v_mul_f32_e32 v41, v41, v6
	v_mul_f32_e32 v34, v34, v5
	v_mul_f32_e32 v35, v35, v4
	v_mul_f32_e32 v36, v36, v7
	v_mul_f32_e32 v37, v37, v6
	v_mul_f32_e32 v0, v0, v5
	v_mul_f32_e32 v1, v1, v4
	v_mul_f32_e32 v2, v2, v7
	v_mul_f32_e32 v3, v3, v6
	v_mul_f32_e32 v4, v29, v30
	v_mul_f32_e32 v71, v71, v96
	v_mul_f32_e32 v72, v72, v95
	v_mul_f32_e32 v73, v73, v97
	v_mul_f32_e32 v5, v29, v31
	v_mul_f32_e32 v6, v29, v32
	v_mul_f32_e32 v7, v29, v33
	v_mul_f32_e32 v29, v28, v38
	v_mul_f32_e32 v30, v28, v39
	v_mul_f32_e32 v31, v28, v40
	v_mul_f32_e32 v28, v28, v41
	v_mul_f32_e32 v32, v27, v34
	v_mul_f32_e32 v33, v27, v35
	v_mul_f32_e32 v34, v27, v36
	v_mul_f32_e32 v27, v27, v37
	v_mul_f32_e32 v0, v26, v0
	v_mul_f32_e32 v1, v26, v1
	v_mul_f32_e32 v2, v26, v2
	v_mul_f32_e32 v3, v26, v3
	v_mul_f32_e32 v4, v8, v4
	v_mul_f32_e32 v5, v61, v5
	v_mul_f32_e32 v6, v63, v6
	v_mul_f32_e32 v7, v64, v7
	v_mul_f32_e32 v8, v62, v29
	v_mul_f32_e32 v26, v65, v30
	v_mul_f32_e32 v29, v66, v31
	v_mul_f32_e32 v28, v67, v28
	v_mul_f32_e32 v30, v74, v32
	v_mul_f32_e32 v31, v68, v33
	v_mul_f32_e32 v32, v69, v34
	v_mul_f32_e32 v27, v70, v27
	v_mul_f32_e32 v0, v60, v0
	v_mul_f32_e32 v1, v71, v1
	v_mul_f32_e32 v2, v72, v2
	v_mul_f32_e32 v3, v73, v3
	v_cndmask_b32_e64 v40, v5, v4, s[72:73]
	v_cndmask_b32_e64 v48, v4, v5, s[72:73]
	v_cndmask_b32_e64 v41, v7, v6, s[72:73]
	v_cndmask_b32_e64 v49, v6, v7, s[72:73]
	v_cndmask_b32_e64 v42, v26, v8, s[72:73]
	v_cndmask_b32_e64 v50, v8, v26, s[72:73]
	v_cndmask_b32_e64 v43, v28, v29, s[72:73]
	v_cndmask_b32_e64 v51, v29, v28, s[72:73]
	v_cndmask_b32_e64 v44, v31, v30, s[72:73]
	v_cndmask_b32_e64 v52, v30, v31, s[72:73]
	v_cndmask_b32_e64 v45, v27, v32, s[72:73]
	v_cndmask_b32_e64 v53, v32, v27, s[72:73]
	v_cndmask_b32_e64 v46, v1, v0, s[72:73]
	v_cndmask_b32_e64 v54, v0, v1, s[72:73]
	v_cndmask_b32_e64 v47, v3, v2, s[72:73]
	v_cndmask_b32_e64 v55, v2, v3, s[72:73]
	v_mov_b32_dpp v56, v48 quad_perm:[1,0,3,2] row_mask:0xf bank_mask:0xf
	v_mov_b32_dpp v57, v49 quad_perm:[1,0,3,2] row_mask:0xf bank_mask:0xf
	v_mov_b32_dpp v58, v50 quad_perm:[1,0,3,2] row_mask:0xf bank_mask:0xf
	v_mov_b32_dpp v59, v51 quad_perm:[1,0,3,2] row_mask:0xf bank_mask:0xf
	v_mov_b32_dpp v60, v52 quad_perm:[1,0,3,2] row_mask:0xf bank_mask:0xf
	v_mov_b32_dpp v61, v53 quad_perm:[1,0,3,2] row_mask:0xf bank_mask:0xf
	v_mov_b32_dpp v62, v54 quad_perm:[1,0,3,2] row_mask:0xf bank_mask:0xf
	v_mov_b32_dpp v63, v55 quad_perm:[1,0,3,2] row_mask:0xf bank_mask:0xf
	v_cndmask_b32_e64 v48, v56, v40, s[72:73]
	v_cndmask_b32_e64 v56, v40, v56, s[72:73]
	v_cndmask_b32_e64 v49, v57, v41, s[72:73]
	v_cndmask_b32_e64 v57, v41, v57, s[72:73]
	v_cndmask_b32_e64 v50, v58, v42, s[72:73]
	v_cndmask_b32_e64 v58, v42, v58, s[72:73]
	v_cndmask_b32_e64 v51, v59, v43, s[72:73]
	v_cndmask_b32_e64 v59, v43, v59, s[72:73]
	v_cndmask_b32_e64 v52, v60, v44, s[72:73]
	v_cndmask_b32_e64 v60, v44, v60, s[72:73]
	v_cndmask_b32_e64 v53, v61, v45, s[72:73]
	v_cndmask_b32_e64 v61, v45, v61, s[72:73]
	v_cndmask_b32_e64 v54, v62, v46, s[72:73]
	v_cndmask_b32_e64 v62, v46, v62, s[72:73]
	v_cndmask_b32_e64 v55, v63, v47, s[72:73]
	v_cndmask_b32_e64 v63, v47, v63, s[72:73]
	v_cvt_pk_bf16_f32 v40, v48, v56
	v_cvt_pk_bf16_f32 v41, v49, v57
	v_cvt_pk_bf16_f32 v42, v50, v58
	v_cvt_pk_bf16_f32 v43, v51, v59
	v_cvt_pk_bf16_f32 v44, v52, v60
	v_cvt_pk_bf16_f32 v45, v53, v61
	v_cvt_pk_bf16_f32 v46, v54, v62
	v_cvt_pk_bf16_f32 v47, v55, v63
	global_store_dword v12, v40, s[20:21]
	global_store_dword v16, v41, s[20:21]
	global_store_dword v13, v42, s[20:21]
	global_store_dword v17, v43, s[20:21]
	global_store_dword v12, v44, s[100:101]
	global_store_dword v16, v45, s[100:101]
	global_store_dword v13, v46, s[100:101]
	global_store_dword v17, v47, s[100:101]
	s_cbranch_scc1 .LBB0_1031
	s_cmp_eq_u32 s96, 1
	s_cbranch_scc0 .LBB0_1032
	s_mov_b32 s96, 2
	s_branch .Lp3b_scan
